# indexer scoring: canonicalising max folded into relu (MFMA results are never signalling NaNs)
# speedup vs baseline: 1.2419x; 1.0051x over previous
.LBB0_621:
	s_add_i32 s30, s37, -9
	s_cmp_ge_i32 s30, s34
	s_cbranch_scc1 .LBB0_632
	s_waitcnt vmcnt(19)
	v_mfma_f32_16x16x32_bf16 v[228:231], v[0:3], v[92:95], 0
	v_mfma_f32_16x16x32_bf16 v[92:95], v[12:15], v[92:95], 0
	s_waitcnt vmcnt(18)
	v_mfma_f32_16x16x32_bf16 v[228:231], v[4:7], v[88:91], v[228:231]
	v_mfma_f32_16x16x32_bf16 v[88:91], v[16:19], v[88:91], v[92:95]
	s_nop 6
	v_max_f32_e32 v228, 0, v228
	v_max_f32_e32 v229, 0, v229
	v_max_f32_e32 v230, 0, v230
	v_max_f32_e32 v231, 0, v231
	v_pk_mul_f32 v[228:229], v[8:9], v[228:229]
	v_pk_mul_f32 v[230:231], v[10:11], v[230:231]
	v_add_f32_e32 v135, v228, v229
	v_add_f32_e32 v135, v230, v135
	v_max_f32_e32 v88, 0, v88
	v_max_f32_e32 v89, 0, v89
	v_add_f32_e32 v135, v231, v135
	v_pk_mul_f32 v[88:89], v[20:21], v[88:89]
	v_max_f32_e32 v90, 0, v90
	v_max_f32_e32 v91, 0, v91
	v_cvt_f16_f32_e32 v135, v135
	v_pk_mul_f32 v[90:91], v[22:23], v[90:91]
	v_add_f32_e32 v88, v88, v89
	v_add_f32_e32 v88, v90, v88
	v_add_f32_e32 v88, v91, v88
	v_cvt_f16_f32_e32 v88, v88
	v_cmp_ne_u16_e32 vcc, s33, v135
	s_nop 1
	v_cndmask_b32_e32 v135, 0, v135, vcc
	v_cmp_lt_i16_e32 vcc, -1, v135
	s_nop 1
	v_cndmask_b32_e32 v89, -1, v222, vcc
	v_cmp_ne_u16_e32 vcc, s33, v88
	v_xor_b32_e32 v89, v89, v135
	ds_write_b16 v122, v89
	v_cndmask_b32_e32 v88, 0, v88, vcc
	v_cmp_lt_i16_e32 vcc, -1, v88
	s_nop 1
	v_cndmask_b32_e32 v89, -1, v222, vcc
	v_xor_b32_e32 v88, v89, v88
	ds_write_b16 v122, v88 offset:32768
	s_add_i32 s30, s37, -8
	s_cmp_ge_i32 s30, s34
	s_cbranch_scc0 .LBB0_633

.LBB0_624:
	s_waitcnt vmcnt(15)
	v_mfma_f32_16x16x32_bf16 v[72:75], v[0:3], v[60:63], 0
	v_mfma_f32_16x16x32_bf16 v[60:63], v[12:15], v[60:63], 0
	s_waitcnt vmcnt(14)
	v_mfma_f32_16x16x32_bf16 v[72:75], v[4:7], v[56:59], v[72:75]
	v_mfma_f32_16x16x32_bf16 v[56:59], v[16:19], v[56:59], v[60:63]
	s_nop 6
	v_max_f32_e32 v72, 0, v72
	v_max_f32_e32 v73, 0, v73
	v_max_f32_e32 v74, 0, v74
	v_max_f32_e32 v75, 0, v75
	v_pk_mul_f32 v[72:73], v[8:9], v[72:73]
	v_pk_mul_f32 v[74:75], v[10:11], v[74:75]
	v_add_f32_e32 v72, v72, v73
	v_add_f32_e32 v72, v74, v72
	v_max_f32_e32 v56, 0, v56
	v_max_f32_e32 v57, 0, v57
	v_add_f32_e32 v72, v75, v72
	v_pk_mul_f32 v[56:57], v[20:21], v[56:57]
	v_max_f32_e32 v58, 0, v58
	v_max_f32_e32 v59, 0, v59
	v_cvt_f16_f32_e32 v72, v72
	v_pk_mul_f32 v[58:59], v[22:23], v[58:59]
	v_add_f32_e32 v56, v56, v57
	v_add_f32_e32 v56, v58, v56
	v_add_f32_e32 v56, v59, v56
	v_cvt_f16_f32_e32 v56, v56
	v_cmp_ne_u16_e32 vcc, s33, v72
	s_nop 1
	v_cndmask_b32_e32 v72, 0, v72, vcc
	v_cmp_lt_i16_e32 vcc, -1, v72
	s_nop 1
	v_cndmask_b32_e32 v57, -1, v222, vcc
	v_cmp_ne_u16_e32 vcc, s33, v56
	v_xor_b32_e32 v57, v57, v72
	ds_write_b16 v122, v57 offset:256
	v_cndmask_b32_e32 v56, 0, v56, vcc
	v_cmp_lt_i16_e32 vcc, -1, v56
	s_nop 1
	v_cndmask_b32_e32 v57, -1, v222, vcc
	v_xor_b32_e32 v56, v57, v56
	ds_write_b16 v122, v56 offset:33024
	s_add_i32 s30, s37, -6
	s_cmp_ge_i32 s30, s34
	s_cbranch_scc0 .LBB0_635

.LBB0_626:
	s_waitcnt vmcnt(11)
	v_mfma_f32_16x16x32_bf16 v[40:43], v[0:3], v[28:31], 0
	v_mfma_f32_16x16x32_bf16 v[28:31], v[12:15], v[28:31], 0
	s_waitcnt vmcnt(10)
	v_mfma_f32_16x16x32_bf16 v[40:43], v[4:7], v[24:27], v[40:43]
	v_mfma_f32_16x16x32_bf16 v[24:27], v[16:19], v[24:27], v[28:31]
	s_nop 6
	v_max_f32_e32 v40, 0, v40
	v_max_f32_e32 v41, 0, v41
	v_max_f32_e32 v42, 0, v42
	v_max_f32_e32 v43, 0, v43
	v_pk_mul_f32 v[40:41], v[8:9], v[40:41]
	v_pk_mul_f32 v[42:43], v[10:11], v[42:43]
	v_add_f32_e32 v40, v40, v41
	v_add_f32_e32 v40, v42, v40
	v_max_f32_e32 v24, 0, v24
	v_max_f32_e32 v25, 0, v25
	v_add_f32_e32 v40, v43, v40
	v_pk_mul_f32 v[24:25], v[20:21], v[24:25]
	v_max_f32_e32 v26, 0, v26
	v_max_f32_e32 v27, 0, v27
	v_cvt_f16_f32_e32 v40, v40
	v_pk_mul_f32 v[26:27], v[22:23], v[26:27]
	v_add_f32_e32 v24, v24, v25
	v_add_f32_e32 v24, v26, v24
	v_add_f32_e32 v24, v27, v24
	v_cvt_f16_f32_e32 v24, v24
	v_cmp_ne_u16_e32 vcc, s33, v40
	s_nop 1
	v_cndmask_b32_e32 v40, 0, v40, vcc
	v_cmp_lt_i16_e32 vcc, -1, v40
	s_nop 1
	v_cndmask_b32_e32 v25, -1, v222, vcc
	v_cmp_ne_u16_e32 vcc, s33, v24
	v_xor_b32_e32 v25, v25, v40
	ds_write_b16 v122, v25 offset:512
	v_cndmask_b32_e32 v24, 0, v24, vcc
	v_cmp_lt_i16_e32 vcc, -1, v24
	s_nop 1
	v_cndmask_b32_e32 v25, -1, v222, vcc
	v_xor_b32_e32 v24, v25, v24
	ds_write_b16 v122, v24 offset:33280
.LBB0_627:
	s_add_i32 s30, s37, 1
	s_min_i32 s30, s30, s35
	s_max_i32 s30, s30, 0
	s_lshl_b32 s30, s30, 2
	s_add_i32 s30, s30, s28
	s_lshl_b64 s[38:39], s[30:31], 11
	s_add_i32 s30, s37, 2
	s_min_i32 s30, s30, s35
	s_max_i32 s30, s30, 0
	s_lshl_b32 s30, s30, 2
	s_add_i32 s30, s30, s28
	s_waitcnt vmcnt(10)
	v_lshl_add_u64 v[24:25], v[140:141], 0, s[38:39]
	s_lshl_b64 s[38:39], s[30:31], 11
	s_add_i32 s30, s37, 3
	s_min_i32 s30, s30, s35
	s_max_i32 s30, s30, 0
	s_lshl_b32 s30, s30, 2
	s_add_i32 s30, s30, s28
	global_load_dwordx4 v[92:95], v[24:25], off
	global_load_dwordx4 v[88:91], v[24:25], off offset:1024
	v_lshl_add_u64 v[24:25], v[140:141], 0, s[38:39]
	s_lshl_b64 s[38:39], s[30:31], 11
	s_add_i32 s30, s37, 4
	s_min_i32 s30, s30, s35
	s_max_i32 s30, s30, 0
	s_lshl_b32 s30, s30, 2
	s_add_i32 s30, s30, s28
	global_load_dwordx4 v[76:79], v[24:25], off
	global_load_dwordx4 v[72:75], v[24:25], off offset:1024
	v_lshl_add_u64 v[24:25], v[140:141], 0, s[38:39]
	s_lshl_b64 s[38:39], s[30:31], 11
	s_add_i32 s30, s37, 5
	s_min_i32 s30, s30, s35
	s_max_i32 s30, s30, 0
	s_lshl_b32 s30, s30, 2
	s_add_i32 s30, s30, s28
	global_load_dwordx4 v[60:63], v[24:25], off
	global_load_dwordx4 v[56:59], v[24:25], off offset:1024
	v_lshl_add_u64 v[24:25], v[140:141], 0, s[38:39]
	s_lshl_b64 s[38:39], s[30:31], 11
	global_load_dwordx4 v[44:47], v[24:25], off
	global_load_dwordx4 v[40:43], v[24:25], off offset:1024
	v_lshl_add_u64 v[24:25], v[140:141], 0, s[38:39]
	global_load_dwordx4 v[28:31], v[24:25], off
	s_nop 0
	global_load_dwordx4 v[24:27], v[24:25], off offset:1024
	s_add_i32 s30, s37, -4
	s_cmp_ge_i32 s30, s34
	s_cbranch_scc1 .LBB0_636
	s_waitcnt vmcnt(19)
	v_mfma_f32_16x16x32_bf16 v[228:231], v[0:3], v[100:103], 0
	v_mfma_f32_16x16x32_bf16 v[100:103], v[12:15], v[100:103], 0
	s_waitcnt vmcnt(18)
	v_mfma_f32_16x16x32_bf16 v[228:231], v[4:7], v[96:99], v[228:231]
	v_mfma_f32_16x16x32_bf16 v[96:99], v[16:19], v[96:99], v[100:103]
	s_nop 6
	v_max_f32_e32 v228, 0, v228
	v_max_f32_e32 v229, 0, v229
	v_max_f32_e32 v230, 0, v230
	v_max_f32_e32 v231, 0, v231
	v_pk_mul_f32 v[228:229], v[8:9], v[228:229]
	v_pk_mul_f32 v[230:231], v[10:11], v[230:231]
	v_add_f32_e32 v135, v228, v229
	v_add_f32_e32 v135, v230, v135
	v_max_f32_e32 v96, 0, v96
	v_max_f32_e32 v97, 0, v97
	v_add_f32_e32 v135, v231, v135
	v_pk_mul_f32 v[96:97], v[20:21], v[96:97]
	v_max_f32_e32 v98, 0, v98
	v_max_f32_e32 v99, 0, v99
	v_cvt_f16_f32_e32 v135, v135
	v_pk_mul_f32 v[98:99], v[22:23], v[98:99]
	v_add_f32_e32 v96, v96, v97
	v_add_f32_e32 v96, v98, v96
	v_add_f32_e32 v96, v99, v96
	v_cvt_f16_f32_e32 v96, v96
	v_cmp_ne_u16_e32 vcc, s33, v135
	s_nop 1
	v_cndmask_b32_e32 v135, 0, v135, vcc
	v_cmp_lt_i16_e32 vcc, -1, v135
	s_nop 1
	v_cndmask_b32_e32 v97, -1, v222, vcc
	v_cmp_ne_u16_e32 vcc, s33, v96
	v_xor_b32_e32 v97, v97, v135
	ds_write_b16 v122, v97 offset:640
	v_cndmask_b32_e32 v96, 0, v96, vcc
	v_cmp_lt_i16_e32 vcc, -1, v96
	s_nop 1
	v_cndmask_b32_e32 v97, -1, v222, vcc
	v_xor_b32_e32 v96, v97, v96
	ds_write_b16 v122, v96 offset:33408
	s_add_i32 s30, s37, -3
	s_cmp_ge_i32 s30, s34
	s_cbranch_scc0 .LBB0_637

.LBB0_630:
	s_waitcnt vmcnt(15)
	v_mfma_f32_16x16x32_bf16 v[80:83], v[0:3], v[68:71], 0
	v_mfma_f32_16x16x32_bf16 v[68:71], v[12:15], v[68:71], 0
	s_waitcnt vmcnt(14)
	v_mfma_f32_16x16x32_bf16 v[80:83], v[4:7], v[64:67], v[80:83]
	v_mfma_f32_16x16x32_bf16 v[64:67], v[16:19], v[64:67], v[68:71]
	s_nop 6
	v_max_f32_e32 v80, 0, v80
	v_max_f32_e32 v81, 0, v81
	v_max_f32_e32 v82, 0, v82
	v_max_f32_e32 v83, 0, v83
	v_pk_mul_f32 v[80:81], v[8:9], v[80:81]
	v_pk_mul_f32 v[82:83], v[10:11], v[82:83]
	v_add_f32_e32 v80, v80, v81
	v_add_f32_e32 v80, v82, v80
	v_max_f32_e32 v64, 0, v64
	v_max_f32_e32 v65, 0, v65
	v_add_f32_e32 v80, v83, v80
	v_pk_mul_f32 v[64:65], v[20:21], v[64:65]
	v_max_f32_e32 v66, 0, v66
	v_max_f32_e32 v67, 0, v67
	v_cvt_f16_f32_e32 v80, v80
	v_pk_mul_f32 v[66:67], v[22:23], v[66:67]
	v_add_f32_e32 v64, v64, v65
	v_add_f32_e32 v64, v66, v64
	v_add_f32_e32 v64, v67, v64
	v_cvt_f16_f32_e32 v64, v64
	v_cmp_ne_u16_e32 vcc, s33, v80
	s_nop 1
	v_cndmask_b32_e32 v80, 0, v80, vcc
	v_cmp_lt_i16_e32 vcc, -1, v80
	s_nop 1
	v_cndmask_b32_e32 v65, -1, v222, vcc
	v_cmp_ne_u16_e32 vcc, s33, v64
	v_xor_b32_e32 v65, v65, v80
	ds_write_b16 v122, v65 offset:896
	v_cndmask_b32_e32 v64, 0, v64, vcc
	v_cmp_lt_i16_e32 vcc, -1, v64
	s_nop 1
	v_cndmask_b32_e32 v65, -1, v222, vcc
	v_xor_b32_e32 v64, v65, v64
	ds_write_b16 v122, v64 offset:33664
	s_add_i32 s30, s37, -1
	s_cmp_ge_i32 s30, s34
	s_cbranch_scc0 .LBB0_639

.LBB0_633:
	s_waitcnt vmcnt(17)
	v_mfma_f32_16x16x32_bf16 v[88:91], v[0:3], v[76:79], 0
	v_mfma_f32_16x16x32_bf16 v[76:79], v[12:15], v[76:79], 0
	s_waitcnt vmcnt(16)
	v_mfma_f32_16x16x32_bf16 v[88:91], v[4:7], v[72:75], v[88:91]
	v_mfma_f32_16x16x32_bf16 v[72:75], v[16:19], v[72:75], v[76:79]
	s_nop 6
	v_max_f32_e32 v88, 0, v88
	v_max_f32_e32 v89, 0, v89
	v_max_f32_e32 v90, 0, v90
	v_max_f32_e32 v91, 0, v91
	v_pk_mul_f32 v[88:89], v[8:9], v[88:89]
	v_pk_mul_f32 v[90:91], v[10:11], v[90:91]
	v_add_f32_e32 v88, v88, v89
	v_add_f32_e32 v88, v90, v88
	v_max_f32_e32 v72, 0, v72
	v_max_f32_e32 v73, 0, v73
	v_add_f32_e32 v88, v91, v88
	v_pk_mul_f32 v[72:73], v[20:21], v[72:73]
	v_max_f32_e32 v74, 0, v74
	v_max_f32_e32 v75, 0, v75
	v_cvt_f16_f32_e32 v88, v88
	v_pk_mul_f32 v[74:75], v[22:23], v[74:75]
	v_add_f32_e32 v72, v72, v73
	v_add_f32_e32 v72, v74, v72
	v_add_f32_e32 v72, v75, v72
	v_cvt_f16_f32_e32 v72, v72
	v_cmp_ne_u16_e32 vcc, s33, v88
	s_nop 1
	v_cndmask_b32_e32 v88, 0, v88, vcc
	v_cmp_lt_i16_e32 vcc, -1, v88
	s_nop 1
	v_cndmask_b32_e32 v73, -1, v222, vcc
	v_cmp_ne_u16_e32 vcc, s33, v72
	v_xor_b32_e32 v73, v73, v88
	ds_write_b16 v122, v73 offset:128
	v_cndmask_b32_e32 v72, 0, v72, vcc
	v_cmp_lt_i16_e32 vcc, -1, v72
	s_nop 1
	v_cndmask_b32_e32 v73, -1, v222, vcc
	v_xor_b32_e32 v72, v73, v72
	ds_write_b16 v122, v72 offset:32896
	s_add_i32 s30, s37, -7
	s_cmp_ge_i32 s30, s34
	s_cbranch_scc0 .LBB0_624

.LBB0_635:
	s_waitcnt vmcnt(13)
	v_mfma_f32_16x16x32_bf16 v[56:59], v[0:3], v[44:47], 0
	v_mfma_f32_16x16x32_bf16 v[44:47], v[12:15], v[44:47], 0
	s_waitcnt vmcnt(12)
	v_mfma_f32_16x16x32_bf16 v[56:59], v[4:7], v[40:43], v[56:59]
	v_mfma_f32_16x16x32_bf16 v[40:43], v[16:19], v[40:43], v[44:47]
	s_nop 6
	v_max_f32_e32 v56, 0, v56
	v_max_f32_e32 v57, 0, v57
	v_max_f32_e32 v58, 0, v58
	v_max_f32_e32 v59, 0, v59
	v_pk_mul_f32 v[56:57], v[8:9], v[56:57]
	v_pk_mul_f32 v[58:59], v[10:11], v[58:59]
	v_add_f32_e32 v56, v56, v57
	v_add_f32_e32 v56, v58, v56
	v_max_f32_e32 v40, 0, v40
	v_max_f32_e32 v41, 0, v41
	v_add_f32_e32 v56, v59, v56
	v_pk_mul_f32 v[40:41], v[20:21], v[40:41]
	v_max_f32_e32 v42, 0, v42
	v_max_f32_e32 v43, 0, v43
	v_cvt_f16_f32_e32 v56, v56
	v_pk_mul_f32 v[42:43], v[22:23], v[42:43]
	v_add_f32_e32 v40, v40, v41
	v_add_f32_e32 v40, v42, v40
	v_add_f32_e32 v40, v43, v40
	v_cvt_f16_f32_e32 v40, v40
	v_cmp_ne_u16_e32 vcc, s33, v56
	s_nop 1
	v_cndmask_b32_e32 v56, 0, v56, vcc
	v_cmp_lt_i16_e32 vcc, -1, v56
	s_nop 1
	v_cndmask_b32_e32 v41, -1, v222, vcc
	v_cmp_ne_u16_e32 vcc, s33, v40
	v_xor_b32_e32 v41, v41, v56
	ds_write_b16 v122, v41 offset:384
	v_cndmask_b32_e32 v40, 0, v40, vcc
	v_cmp_lt_i16_e32 vcc, -1, v40
	s_nop 1
	v_cndmask_b32_e32 v41, -1, v222, vcc
	v_xor_b32_e32 v40, v41, v40
	ds_write_b16 v122, v40 offset:33152
	s_add_i32 s30, s37, -5
	s_cmp_ge_i32 s30, s34
	s_cbranch_scc0 .LBB0_626
	s_branch .LBB0_627

.LBB0_637:
	s_waitcnt vmcnt(17)
	v_mfma_f32_16x16x32_bf16 v[96:99], v[0:3], v[84:87], 0
	v_mfma_f32_16x16x32_bf16 v[84:87], v[12:15], v[84:87], 0
	s_waitcnt vmcnt(16)
	v_mfma_f32_16x16x32_bf16 v[96:99], v[4:7], v[80:83], v[96:99]
	v_mfma_f32_16x16x32_bf16 v[80:83], v[16:19], v[80:83], v[84:87]
	s_nop 6
	v_max_f32_e32 v96, 0, v96
	v_max_f32_e32 v97, 0, v97
	v_max_f32_e32 v98, 0, v98
	v_max_f32_e32 v99, 0, v99
	v_pk_mul_f32 v[96:97], v[8:9], v[96:97]
	v_pk_mul_f32 v[98:99], v[10:11], v[98:99]
	v_add_f32_e32 v96, v96, v97
	v_add_f32_e32 v96, v98, v96
	v_max_f32_e32 v80, 0, v80
	v_max_f32_e32 v81, 0, v81
	v_add_f32_e32 v96, v99, v96
	v_pk_mul_f32 v[80:81], v[20:21], v[80:81]
	v_max_f32_e32 v82, 0, v82
	v_max_f32_e32 v83, 0, v83
	v_cvt_f16_f32_e32 v96, v96
	v_pk_mul_f32 v[82:83], v[22:23], v[82:83]
	v_add_f32_e32 v80, v80, v81
	v_add_f32_e32 v80, v82, v80
	v_add_f32_e32 v80, v83, v80
	v_cvt_f16_f32_e32 v80, v80
	v_cmp_ne_u16_e32 vcc, s33, v96
	s_nop 1
	v_cndmask_b32_e32 v96, 0, v96, vcc
	v_cmp_lt_i16_e32 vcc, -1, v96
	s_nop 1
	v_cndmask_b32_e32 v81, -1, v222, vcc
	v_cmp_ne_u16_e32 vcc, s33, v80
	v_xor_b32_e32 v81, v81, v96
	ds_write_b16 v122, v81 offset:768
	v_cndmask_b32_e32 v80, 0, v80, vcc
	v_cmp_lt_i16_e32 vcc, -1, v80
	s_nop 1
	v_cndmask_b32_e32 v81, -1, v222, vcc
	v_xor_b32_e32 v80, v81, v80
	ds_write_b16 v122, v80 offset:33536
	s_add_i32 s30, s37, -2
	s_cmp_ge_i32 s30, s34
	s_cbranch_scc0 .LBB0_630

.LBB0_639:
	s_waitcnt vmcnt(13)
	v_mfma_f32_16x16x32_bf16 v[64:67], v[0:3], v[52:55], 0
	v_mfma_f32_16x16x32_bf16 v[52:55], v[12:15], v[52:55], 0
	s_waitcnt vmcnt(12)
	v_mfma_f32_16x16x32_bf16 v[64:67], v[4:7], v[48:51], v[64:67]
	v_mfma_f32_16x16x32_bf16 v[48:51], v[16:19], v[48:51], v[52:55]
	s_nop 6
	v_max_f32_e32 v64, 0, v64
	v_max_f32_e32 v65, 0, v65
	v_max_f32_e32 v66, 0, v66
	v_max_f32_e32 v67, 0, v67
	v_pk_mul_f32 v[64:65], v[8:9], v[64:65]
	v_pk_mul_f32 v[66:67], v[10:11], v[66:67]
	v_add_f32_e32 v64, v64, v65
	v_add_f32_e32 v64, v66, v64
	v_max_f32_e32 v48, 0, v48
	v_max_f32_e32 v49, 0, v49
	v_add_f32_e32 v64, v67, v64
	v_pk_mul_f32 v[48:49], v[20:21], v[48:49]
	v_max_f32_e32 v50, 0, v50
	v_max_f32_e32 v51, 0, v51
	v_cvt_f16_f32_e32 v64, v64
	v_pk_mul_f32 v[50:51], v[22:23], v[50:51]
	v_add_f32_e32 v48, v48, v49
	v_add_f32_e32 v48, v50, v48
	v_add_f32_e32 v48, v51, v48
	v_cvt_f16_f32_e32 v48, v48
	v_cmp_ne_u16_e32 vcc, s33, v64
	s_nop 1
	v_cndmask_b32_e32 v64, 0, v64, vcc
	v_cmp_lt_i16_e32 vcc, -1, v64
	s_nop 1
	v_cndmask_b32_e32 v49, -1, v222, vcc
	v_cmp_ne_u16_e32 vcc, s33, v48
	v_xor_b32_e32 v49, v49, v64
	ds_write_b16 v122, v49 offset:1024
	v_cndmask_b32_e32 v48, 0, v48, vcc
	v_cmp_lt_i16_e32 vcc, -1, v48
	s_nop 1
	v_cndmask_b32_e32 v49, -1, v222, vcc
	v_xor_b32_e32 v48, v49, v48
	ds_write_b16 v122, v48 offset:33792
	s_cmp_ge_i32 s37, s34
	s_cbranch_scc1 .LBB0_620
.LBB0_640:
	s_waitcnt vmcnt(11)
	v_mfma_f32_16x16x32_bf16 v[48:51], v[0:3], v[36:39], 0
	v_mfma_f32_16x16x32_bf16 v[36:39], v[12:15], v[36:39], 0
	s_waitcnt vmcnt(10)
	v_mfma_f32_16x16x32_bf16 v[48:51], v[4:7], v[32:35], v[48:51]
	v_mfma_f32_16x16x32_bf16 v[32:35], v[16:19], v[32:35], v[36:39]
	s_nop 6
	v_max_f32_e32 v48, 0, v48
	v_max_f32_e32 v49, 0, v49
	v_max_f32_e32 v50, 0, v50
	v_max_f32_e32 v51, 0, v51
	v_pk_mul_f32 v[48:49], v[8:9], v[48:49]
	v_pk_mul_f32 v[50:51], v[10:11], v[50:51]
	v_add_f32_e32 v48, v48, v49
	v_add_f32_e32 v48, v50, v48
	v_max_f32_e32 v32, 0, v32
	v_max_f32_e32 v33, 0, v33
	v_add_f32_e32 v48, v51, v48
	v_pk_mul_f32 v[32:33], v[20:21], v[32:33]
	v_max_f32_e32 v34, 0, v34
	v_max_f32_e32 v35, 0, v35
	v_cvt_f16_f32_e32 v48, v48
	v_pk_mul_f32 v[34:35], v[22:23], v[34:35]
	v_add_f32_e32 v32, v32, v33
	v_add_f32_e32 v32, v34, v32
	v_add_f32_e32 v32, v35, v32
	v_cvt_f16_f32_e32 v32, v32
	v_cmp_ne_u16_e32 vcc, s33, v48
	s_nop 1
	v_cndmask_b32_e32 v48, 0, v48, vcc
	v_cmp_lt_i16_e32 vcc, -1, v48
	s_nop 1
	v_cndmask_b32_e32 v33, -1, v222, vcc
	v_cmp_ne_u16_e32 vcc, s33, v32
	v_xor_b32_e32 v33, v33, v48
	ds_write_b16 v122, v33 offset:1152
	v_cndmask_b32_e32 v32, 0, v32, vcc
	v_cmp_lt_i16_e32 vcc, -1, v32
	s_nop 1
	v_cndmask_b32_e32 v33, -1, v222, vcc
	v_xor_b32_e32 v32, v33, v32
	ds_write_b16 v122, v32 offset:33920
	s_branch .LBB0_620
